# speedup vs baseline: 1.0545x; 1.0140x over previous
; __device__ __forceinline__ int tid_opaque() { int t = threadIdx.x; asm volatile("" : "+v"(t)); return t; }
; __device__ __forceinline__ unsigned xb_add(unsigned* p, unsigned v) { return __hip_atomic_fetch_add(p, v, __ATOMIC_RELAXED, __HIP_MEMORY_SCOPE_AGENT); }
; __device__ __forceinline__ void xcd_barrier(const XcdBarrier& b, unsigned epoch) {
;     asm volatile("s_waitcnt vmcnt(0)" ::: "memory");
;     __syncthreads();
;     if (tid_opaque() == 0) {
;         unsigned* bar = b.bar;
;         unsigned bx = b.x, bnloc = b.nloc, bnx = b.nx;
;         asm volatile("" : "+s"(bar), "+s"(bx), "+s"(bnloc), "+s"(bnx));
;         __builtin_amdgcn_s_waitcnt(0);
;         const unsigned old = xb_add(&bar[XB_XSUB(bx)], 1u);
;         const unsigned gen = epoch;
;         if (old + 1u == (gen + 1u) * bnloc) {
; __global__ void __launch_bounds__(512, 2) mega(Params p) {
;     ...
;         const unsigned e0 = 1u + 5u * (unsigned)l;
;         phase_A(p, l);
;         xcd_barrier(xb, e0);
.LBB0_133:
	s_waitcnt vmcnt(0)
	v_readlane_b32 s0, v234, 46
	v_mov_b32_e32 v0, v208
	s_mul_i32 s0, s0, 3
	s_barrier
	v_writelane_b32 v234, s0, 60
	v_cmp_eq_u32_e32 vcc, 0, v0
	s_and_saveexec_b64 s[0:1], vcc
	s_cbranch_execz .LBB0_163
	s_mov_b32 s4, s51
	v_readlane_b32 s26, v234, 3
	s_mov_b64 s[2:3], s[92:93]
	v_readlane_b32 s6, v234, 2
	s_lshl_b32 s24, s4, 6
	v_readlane_b32 s7, v234, 60
	s_add_i32 s72, s24, 0x500
	s_add_i32 s25, s7, 1
	s_lshl_b64 s[4:5], s[72:73], 2
	s_add_u32 s4, s2, s4
	s_addc_u32 s5, s3, s5
	v_mov_b64_e32 v[0:1], s[4:5]
	s_waitcnt vmcnt(0) expcnt(0) lgkmcnt(0)
	flat_atomic_add v0, v[0:1], v210 sc0
	s_add_i32 s27, s7, 2
	s_mul_i32 s6, s6, s27
	s_waitcnt vmcnt(0) lgkmcnt(0)
	v_add_u32_e32 v0, 1, v0
	v_cmp_ne_u32_e32 vcc, s6, v0
	s_and_saveexec_b64 s[4:5], vcc
	s_xor_b64 s[4:5], exec, s[4:5]
	s_cbranch_execz .LBB0_147
	s_add_i32 s72, s24, 0x900
	s_lshl_b64 s[6:7], s[72:73], 2
	s_add_u32 s8, s2, s6
	s_addc_u32 s9, s3, s7
	v_mov_b64_e32 v[0:1], s[8:9]
	flat_load_dword v0, v[0:1] sc1
	s_waitcnt vmcnt(0) lgkmcnt(0)
	v_cmp_eq_u32_e32 vcc, s25, v0
	s_and_saveexec_b64 s[6:7], vcc
	s_cbranch_execz .LBB0_146
	s_mov_b32 s28, 1
	s_mov_b64 s[10:11], 0
	s_branch .LBB0_138

; __device__ __forceinline__ int tid_opaque() { int t = threadIdx.x; asm volatile("" : "+v"(t)); return t; }
; __device__ __forceinline__ unsigned xb_ld(unsigned* p) { return __hip_atomic_load(p, __ATOMIC_RELAXED, __HIP_MEMORY_SCOPE_AGENT); }
; __device__ __forceinline__ unsigned xb_add(unsigned* p, unsigned v) { return __hip_atomic_fetch_add(p, v, __ATOMIC_RELAXED, __HIP_MEMORY_SCOPE_AGENT); }
; __device__ __forceinline__ void xcd_barrier(const XcdBarrier& b, unsigned epoch) {
;     asm volatile("s_waitcnt vmcnt(0)" ::: "memory");
;     __syncthreads();
;     if (tid_opaque() == 0) {
;         unsigned* bar = b.bar;
;         unsigned bx = b.x, bnloc = b.nloc, bnx = b.nx;
;         asm volatile("" : "+s"(bar), "+s"(bx), "+s"(bnloc), "+s"(bnx));
;         __builtin_amdgcn_s_waitcnt(0);
;         const unsigned old = xb_add(&bar[XB_XSUB(bx)], 1u);
;         const unsigned gen = epoch;
;         if (old + 1u == (gen + 1u) * bnloc) {
;             __builtin_amdgcn_fence(__ATOMIC_RELEASE, "agent");
;             asm volatile("s_waitcnt vmcnt(0)" ::: "memory");
;             const unsigned og = xb_add(&bar[XB_TOP], 1u);
;             const unsigned tg = epoch;
;             if (og + 1u == (tg + 1u) * bnx) xb_add(&bar[XB_TOPGEN], 1u);
;             else XB_SPIN(xb_ld(&bar[XB_TOPGEN]) == tg, bar);
;             __builtin_amdgcn_fence(__ATOMIC_ACQUIRE, "agent");
;             xb_add(&bar[XB_XGEN(bx)], 1u);
;         } else {
;             XB_SPIN(xb_ld(&bar[XB_XGEN(bx)]) == gen, bar);
;             __builtin_amdgcn_fence(__ATOMIC_ACQUIRE, "agent");
;         }
;     }
;     __syncthreads();
; }
; __global__ void __launch_bounds__(512, 2) mega(Params p) {
;     ...
;         phase_GC(p, l);
;         xcd_barrier(xb, e0 + 2u);
.LBB0_367:
	s_waitcnt vmcnt(0)
	v_mov_b32_e32 v0, v208
	s_barrier
	s_nop 0
	v_cmp_eq_u32_e32 vcc, 0, v0
	s_and_saveexec_b64 s[0:1], vcc
	s_cbranch_execz .LBB0_456
	v_readlane_b32 s4, v234, 46
	s_lshl_b32 s4, s4, 7
	s_and_b32 s5, s50, 63
	s_add_i32 s4, s4, s5
	s_add_i32 s4, s4, 0
	s_lshl_b32 s4, s4, 6
	s_add_i32 s4, s4, 0x4000
	s_add_u32 s4, s92, s4
	s_addc_u32 s5, s93, 0
	v_mov_b32_e32 v0, 0
	s_waitcnt vmcnt(0) lgkmcnt(0)
	global_atomic_add v0, v210, s[4:5]
	s_waitcnt vmcnt(0)
.Lgba_spin:
	global_load_dword v1, v0, s[4:5] sc1
	s_waitcnt vmcnt(0)
	v_cmp_gt_u32_e32 vcc, 4, v1
	s_cbranch_vccz .Lgba_done
	s_sleep 1
	s_branch .Lgba_spin
.Lgba_done:
	buffer_inv sc1
	s_branch .LBB0_456
	s_mov_b32 s4, s51
	v_readlane_b32 s28, v234, 3
	s_mov_b64 s[2:3], s[92:93]
	v_readlane_b32 s6, v234, 2
	s_lshl_b32 s26, s4, 6
	v_readlane_b32 s7, v234, 60
	s_add_i32 s72, s26, 0x500
	s_add_i32 s27, s7, 3
	s_lshl_b64 s[4:5], s[72:73], 2
	s_add_u32 s4, s2, s4
	s_addc_u32 s5, s3, s5
	v_mov_b64_e32 v[0:1], s[4:5]
	s_waitcnt vmcnt(0) expcnt(0) lgkmcnt(0)
	flat_atomic_add v0, v[0:1], v210 sc0
	s_add_i32 s29, s7, 4
	s_mul_i32 s6, s6, s29
	s_waitcnt vmcnt(0) lgkmcnt(0)
	v_add_u32_e32 v0, 1, v0
	v_cmp_ne_u32_e32 vcc, s6, v0
	s_and_saveexec_b64 s[4:5], vcc
	s_xor_b64 s[4:5], exec, s[4:5]
	s_cbranch_execz .LBB0_440
	s_add_i32 s72, s26, 0x900
	s_lshl_b64 s[6:7], s[72:73], 2
	s_add_u32 s10, s2, s6
	s_addc_u32 s11, s3, s7
	v_mov_b64_e32 v[0:1], s[10:11]
	flat_load_dword v0, v[0:1] sc1
	s_waitcnt vmcnt(0) lgkmcnt(0)
	v_cmp_eq_u32_e32 vcc, s27, v0
	s_and_saveexec_b64 s[6:7], vcc
	s_cbranch_execz .LBB0_439
	s_mov_b32 s30, 1
	s_mov_b64 s[12:13], 0
	s_branch .LBB0_431

; __device__ __forceinline__ int tid_opaque() { int t = threadIdx.x; asm volatile("" : "+v"(t)); return t; }
; __device__ __forceinline__ void phase_D(const Params& p, int l) {
;     ...
;         {
;             const int et = tid_opaque();
;             const int wr = (et >> 8) & 1, wc = (et >> 6) & 3, fr = et & 15, fq = (et >> 4) & 3;
; #pragma unroll
;             for (int ai = 0; ai < 2; ++ai)
; #pragma unroll
;                 for (int m = 0; m < 4; ++m) {
;                     int row = brow + ai * 128 + wr * 64 + m * 16 + fr;
;                     float ss = 0.f;
; #pragma unroll
;                     for (int bj = 0; bj < 2; ++bj)
; #pragma unroll
;                         for (int n = 0; n < 2; ++n) {
;                             f32x4 a = acc[ai][bj][m][n];
;                             ss += a[0] * a[0] + a[1] * a[1] + a[2] * a[2] + a[3] * a[3];
;                         }
;                     ss += __shfl_xor(ss, 16);
;                     ss += __shfl_xor(ss, 32);
;                     if (fq == 0) PART[(long)row * 16 + pn * 4 + wc] = ss;
;                 }
.LBB0_463:
	s_or_b64 exec, exec, s[0:1]
	v_mov_b32_e32 v128, v208
	v_and_b32_e32 v132, 64, v213
	v_lshrrev_b32_e32 v131, 2, v128
	v_and_b32_e32 v130, 15, v128
	v_and_b32_e32 v131, 64, v131
	v_or3_b32 v130, v130, v131, s6
	v_xor_b32_e32 v131, 16, v213
	v_add_u32_e32 v132, 64, v132
	v_cmp_lt_i32_e32 vcc, v131, v132
	s_lshl_b32 s0, s15, 2
	s_ashr_i32 s1, s0, 31
	v_cndmask_b32_e32 v131, v213, v131, vcc
	v_lshlrev_b32_e32 v134, 2, v131
	v_xor_b32_e32 v131, 32, v213
	v_cmp_lt_i32_e32 vcc, v131, v132
	v_mul_f32_e32 v132, v121, v121
	v_fmac_f32_e32 v132, v120, v120
	v_cndmask_b32_e32 v131, v213, v131, vcc
	v_lshlrev_b32_e32 v135, 2, v131
	v_and_b32_e32 v131, 48, v128
	v_cmp_eq_u32_e32 vcc, 0, v131
	v_mul_f32_e32 v131, v125, v125
	v_fmac_f32_e32 v131, v124, v124
	v_fmac_f32_e32 v131, v126, v126
	v_fmac_f32_e32 v132, v122, v122
	v_fmac_f32_e32 v131, v127, v127
	v_fmac_f32_e32 v132, v123, v123
	v_add_f32_e32 v131, v131, v132
	v_mul_f32_e32 v132, v109, v109
	v_fmac_f32_e32 v132, v108, v108
	v_fmac_f32_e32 v132, v110, v110
	v_fmac_f32_e32 v132, v111, v111
	v_add_f32_e32 v131, v131, v132
	v_mul_f32_e32 v132, v93, v93
	v_fmac_f32_e32 v132, v92, v92
	v_fmac_f32_e32 v132, v94, v94
	v_fmac_f32_e32 v132, v95, v95
	v_add_f32_e32 v131, v131, v132
	ds_bpermute_b32 v132, v134, v131
	s_lshl_b64 s[0:1], s[0:1], 2
	s_add_u32 s0, s96, s0
	v_lshrrev_b32_e32 v128, 4, v128
	s_addc_u32 s1, s97, s1
	s_waitcnt lgkmcnt(0)
	v_add_f32_e32 v136, v131, v132
	ds_bpermute_b32 v137, v135, v136
	v_and_b32_e32 v128, 12, v128
	v_lshl_add_u64 v[132:133], s[0:1], 0, v[128:129]
	s_and_saveexec_b64 s[0:1], vcc
	s_cbranch_execz .LBB0_465
	v_ashrrev_i32_e32 v131, 31, v130
	v_lshlrev_b64 v[138:139], 6, v[130:131]
	v_lshl_add_u64 v[138:139], v[132:133], 0, v[138:139]
	s_waitcnt lgkmcnt(0)
	v_add_f32_e32 v128, v136, v137
	global_store_dword v[138:139], v128, off sc1
.LBB0_465:
	s_or_b64 exec, exec, s[0:1]
	v_mul_f32_e32 v128, v117, v117
	v_mul_f32_e32 v131, v113, v113
	v_fmac_f32_e32 v128, v116, v116
	v_fmac_f32_e32 v131, v112, v112
	v_fmac_f32_e32 v128, v118, v118
	v_fmac_f32_e32 v131, v114, v114
	v_fmac_f32_e32 v128, v119, v119
	v_fmac_f32_e32 v131, v115, v115
	v_add_f32_e32 v128, v128, v131
	v_mul_f32_e32 v131, v85, v85
	v_fmac_f32_e32 v131, v84, v84
	v_fmac_f32_e32 v131, v86, v86
	v_fmac_f32_e32 v131, v87, v87
	v_add_f32_e32 v128, v128, v131
	v_mul_f32_e32 v131, v81, v81
	v_fmac_f32_e32 v131, v80, v80
	v_fmac_f32_e32 v131, v82, v82
	v_fmac_f32_e32 v131, v83, v83
	v_add_f32_e32 v128, v128, v131
	ds_bpermute_b32 v131, v134, v128
	s_waitcnt lgkmcnt(0)
	v_add_f32_e32 v128, v128, v131
	ds_bpermute_b32 v131, v135, v128
	s_and_saveexec_b64 s[0:1], vcc
	s_cbranch_execz .LBB0_467
	v_or_b32_e32 v136, 16, v130
	v_ashrrev_i32_e32 v137, 31, v136
	v_lshlrev_b64 v[136:137], 6, v[136:137]
	v_lshl_add_u64 v[136:137], v[132:133], 0, v[136:137]
	s_waitcnt lgkmcnt(0)
	v_add_f32_e32 v128, v128, v131
	global_store_dword v[136:137], v128, off sc1
.LBB0_467:
	s_or_b64 exec, exec, s[0:1]
	v_mul_f32_e32 v128, v105, v105
	s_waitcnt lgkmcnt(0)
	v_mul_f32_e32 v131, v101, v101
	v_fmac_f32_e32 v128, v104, v104
	v_fmac_f32_e32 v131, v100, v100
	v_fmac_f32_e32 v128, v106, v106
	v_fmac_f32_e32 v131, v102, v102
	v_fmac_f32_e32 v128, v107, v107
	v_fmac_f32_e32 v131, v103, v103
	v_add_f32_e32 v128, v128, v131
	v_mul_f32_e32 v131, v73, v73
	v_fmac_f32_e32 v131, v72, v72
	v_fmac_f32_e32 v131, v74, v74
	v_fmac_f32_e32 v131, v75, v75
	v_add_f32_e32 v128, v128, v131
	v_mul_f32_e32 v131, v69, v69
	v_fmac_f32_e32 v131, v68, v68
	v_fmac_f32_e32 v131, v70, v70
	v_fmac_f32_e32 v131, v71, v71
	v_add_f32_e32 v128, v128, v131
	ds_bpermute_b32 v131, v134, v128
	s_waitcnt lgkmcnt(0)
	v_add_f32_e32 v128, v128, v131
	ds_bpermute_b32 v131, v135, v128
	s_and_saveexec_b64 s[0:1], vcc
	s_cbranch_execz .LBB0_469
	v_or_b32_e32 v136, 32, v130
	v_ashrrev_i32_e32 v137, 31, v136
	v_lshlrev_b64 v[136:137], 6, v[136:137]
	v_lshl_add_u64 v[136:137], v[132:133], 0, v[136:137]
	s_waitcnt lgkmcnt(0)
	v_add_f32_e32 v128, v128, v131
	global_store_dword v[136:137], v128, off sc1
.LBB0_469:
	s_or_b64 exec, exec, s[0:1]
	v_mul_f32_e32 v128, v97, v97
	s_waitcnt lgkmcnt(0)
	v_mul_f32_e32 v131, v89, v89
	v_fmac_f32_e32 v128, v96, v96
	v_fmac_f32_e32 v131, v88, v88
	v_fmac_f32_e32 v128, v98, v98
	v_fmac_f32_e32 v131, v90, v90
	v_fmac_f32_e32 v128, v99, v99
	v_fmac_f32_e32 v131, v91, v91
	v_add_f32_e32 v128, v128, v131
	v_mul_f32_e32 v131, v61, v61
	v_fmac_f32_e32 v131, v60, v60
	v_fmac_f32_e32 v131, v62, v62
	v_fmac_f32_e32 v131, v63, v63
	v_add_f32_e32 v128, v128, v131
	v_mul_f32_e32 v131, v57, v57
	v_fmac_f32_e32 v131, v56, v56
	v_fmac_f32_e32 v131, v58, v58
	v_fmac_f32_e32 v131, v59, v59
	v_add_f32_e32 v128, v128, v131
	ds_bpermute_b32 v131, v134, v128
	s_waitcnt lgkmcnt(0)
	v_add_f32_e32 v128, v128, v131
	ds_bpermute_b32 v131, v135, v128
	s_and_saveexec_b64 s[0:1], vcc
	s_cbranch_execz .LBB0_471
	v_or_b32_e32 v136, 48, v130
	v_ashrrev_i32_e32 v137, 31, v136
	v_lshlrev_b64 v[136:137], 6, v[136:137]
	v_lshl_add_u64 v[136:137], v[132:133], 0, v[136:137]
	s_waitcnt lgkmcnt(0)
	v_add_f32_e32 v128, v128, v131
	global_store_dword v[136:137], v128, off sc1
; __device__ __forceinline__ void phase_D(const Params& p, int l) {
;     ...
; #pragma unroll
;             for (int ai = 0; ai < 2; ++ai)
; #pragma unroll
;                 for (int m = 0; m < 4; ++m) {
;                     int row = brow + ai * 128 + wr * 64 + m * 16 + fr;
;                     float ss = 0.f;
; #pragma unroll
;                     for (int bj = 0; bj < 2; ++bj)
; #pragma unroll
;                         for (int n = 0; n < 2; ++n) {
;                             f32x4 a = acc[ai][bj][m][n];
;                             ss += a[0] * a[0] + a[1] * a[1] + a[2] * a[2] + a[3] * a[3];
;                         }
;                     ss += __shfl_xor(ss, 16);
;                     ss += __shfl_xor(ss, 32);
;                     if (fq == 0) PART[(long)row * 16 + pn * 4 + wc] = ss;
;                 }
.LBB0_471:
	s_or_b64 exec, exec, s[0:1]
	v_mul_f32_e32 v128, v77, v77
	s_waitcnt lgkmcnt(0)
	v_mul_f32_e32 v131, v65, v65
	v_fmac_f32_e32 v128, v76, v76
	v_fmac_f32_e32 v131, v64, v64
	v_fmac_f32_e32 v128, v78, v78
	v_fmac_f32_e32 v131, v66, v66
	v_fmac_f32_e32 v128, v79, v79
	v_fmac_f32_e32 v131, v67, v67
	v_add_f32_e32 v128, v128, v131
	v_mul_f32_e32 v131, v29, v29
	v_fmac_f32_e32 v131, v28, v28
	v_fmac_f32_e32 v131, v30, v30
	v_fmac_f32_e32 v131, v31, v31
	v_add_f32_e32 v128, v128, v131
	v_mul_f32_e32 v131, v25, v25
	v_fmac_f32_e32 v131, v24, v24
	v_fmac_f32_e32 v131, v26, v26
	v_fmac_f32_e32 v131, v27, v27
	v_add_f32_e32 v128, v128, v131
	ds_bpermute_b32 v131, v134, v128
	s_waitcnt lgkmcnt(0)
	v_add_f32_e32 v128, v128, v131
	ds_bpermute_b32 v131, v135, v128
	s_and_saveexec_b64 s[0:1], vcc
	s_cbranch_execz .LBB0_473
	v_or_b32_e32 v136, 0x80, v130
	v_ashrrev_i32_e32 v137, 31, v136
	v_lshlrev_b64 v[136:137], 6, v[136:137]
	v_lshl_add_u64 v[136:137], v[132:133], 0, v[136:137]
	s_waitcnt lgkmcnt(0)
	v_add_f32_e32 v128, v128, v131
	global_store_dword v[136:137], v128, off sc1
.LBB0_473:
	s_or_b64 exec, exec, s[0:1]
	v_mul_f32_e32 v128, v53, v53
	s_waitcnt lgkmcnt(0)
	v_mul_f32_e32 v131, v49, v49
	v_fmac_f32_e32 v128, v52, v52
	v_fmac_f32_e32 v131, v48, v48
	v_fmac_f32_e32 v128, v54, v54
	v_fmac_f32_e32 v131, v50, v50
	v_fmac_f32_e32 v128, v55, v55
	v_fmac_f32_e32 v131, v51, v51
	v_add_f32_e32 v128, v128, v131
	v_mul_f32_e32 v131, v21, v21
	v_fmac_f32_e32 v131, v20, v20
	v_fmac_f32_e32 v131, v22, v22
	v_fmac_f32_e32 v131, v23, v23
	v_add_f32_e32 v128, v128, v131
	v_mul_f32_e32 v131, v17, v17
	v_fmac_f32_e32 v131, v16, v16
	v_fmac_f32_e32 v131, v18, v18
	v_fmac_f32_e32 v131, v19, v19
	v_add_f32_e32 v128, v128, v131
	ds_bpermute_b32 v131, v134, v128
	s_waitcnt lgkmcnt(0)
	v_add_f32_e32 v128, v128, v131
	ds_bpermute_b32 v131, v135, v128
	s_and_saveexec_b64 s[0:1], vcc
	s_cbranch_execz .LBB0_475
	v_or_b32_e32 v136, 0x90, v130
	v_ashrrev_i32_e32 v137, 31, v136
	v_lshlrev_b64 v[136:137], 6, v[136:137]
	v_lshl_add_u64 v[136:137], v[132:133], 0, v[136:137]
	s_waitcnt lgkmcnt(0)
	v_add_f32_e32 v128, v128, v131
	global_store_dword v[136:137], v128, off sc1
.LBB0_475:
	s_or_b64 exec, exec, s[0:1]
	v_mul_f32_e32 v128, v45, v45
	s_waitcnt lgkmcnt(0)
	v_mul_f32_e32 v131, v41, v41
	v_fmac_f32_e32 v128, v44, v44
	v_fmac_f32_e32 v131, v40, v40
	v_fmac_f32_e32 v128, v46, v46
	v_fmac_f32_e32 v131, v42, v42
	v_fmac_f32_e32 v128, v47, v47
	v_fmac_f32_e32 v131, v43, v43
	v_add_f32_e32 v128, v128, v131
	v_mul_f32_e32 v131, v13, v13
	v_fmac_f32_e32 v131, v12, v12
	v_fmac_f32_e32 v131, v14, v14
	v_fmac_f32_e32 v131, v15, v15
	v_add_f32_e32 v128, v128, v131
	v_mul_f32_e32 v131, v9, v9
	v_fmac_f32_e32 v131, v8, v8
	v_fmac_f32_e32 v131, v10, v10
	v_fmac_f32_e32 v131, v11, v11
	v_add_f32_e32 v128, v128, v131
	ds_bpermute_b32 v131, v134, v128
	s_waitcnt lgkmcnt(0)
	v_add_f32_e32 v128, v128, v131
	ds_bpermute_b32 v131, v135, v128
	s_and_saveexec_b64 s[0:1], vcc
	s_cbranch_execz .LBB0_477
	v_or_b32_e32 v136, 0xa0, v130
	v_ashrrev_i32_e32 v137, 31, v136
	v_lshlrev_b64 v[136:137], 6, v[136:137]
	v_lshl_add_u64 v[136:137], v[132:133], 0, v[136:137]
	s_waitcnt lgkmcnt(0)
	v_add_f32_e32 v128, v128, v131
	global_store_dword v[136:137], v128, off sc1
.LBB0_477:
	s_or_b64 exec, exec, s[0:1]
	v_mul_f32_e32 v128, v37, v37
	s_waitcnt lgkmcnt(0)
	v_mul_f32_e32 v131, v33, v33
	v_fmac_f32_e32 v128, v36, v36
	v_fmac_f32_e32 v131, v32, v32
	v_fmac_f32_e32 v128, v38, v38
	v_fmac_f32_e32 v131, v34, v34
	v_fmac_f32_e32 v128, v39, v39
	v_fmac_f32_e32 v131, v35, v35
	v_add_f32_e32 v128, v128, v131
	v_mul_f32_e32 v131, v5, v5
	v_fmac_f32_e32 v131, v4, v4
	v_fmac_f32_e32 v131, v6, v6
	v_fmac_f32_e32 v131, v7, v7
	v_add_f32_e32 v128, v128, v131
	v_mul_f32_e32 v131, v1, v1
	v_fmac_f32_e32 v131, v0, v0
	v_fmac_f32_e32 v131, v2, v2
	v_fmac_f32_e32 v131, v3, v3
	v_add_f32_e32 v128, v128, v131
	ds_bpermute_b32 v131, v134, v128
	s_waitcnt lgkmcnt(0)
	v_add_f32_e32 v128, v128, v131
	ds_bpermute_b32 v131, v135, v128
	s_and_saveexec_b64 s[0:1], vcc
	s_cbranch_execz .LBB0_479
	v_or_b32_e32 v134, 0xb0, v130
	v_ashrrev_i32_e32 v135, 31, v134
	v_lshlrev_b64 v[134:135], 6, v[134:135]
	v_lshl_add_u64 v[132:133], v[132:133], 0, v[134:135]
	s_waitcnt lgkmcnt(0)
	v_add_f32_e32 v128, v128, v131
	global_store_dword v[132:133], v128, off sc1

; __device__ __forceinline__ void xcd_barrier(const XcdBarrier& b, unsigned epoch) {
;     asm volatile("s_waitcnt vmcnt(0)" ::: "memory");
;     __syncthreads();
; __global__ void __launch_bounds__(512, 2) mega(Params p) {
;     ...
;         phase_D(p, l);
;         xcd_barrier(xb, e0 + 3u);
.LBB0_482:
	s_waitcnt vmcnt(0)
	v_mov_b32_e32 v0, v208
	s_barrier
	s_nop 0
	v_cmp_eq_u32_e32 vcc, 0, v0
	s_and_saveexec_b64 s[0:1], vcc
	s_cbranch_execz .LBB0_512
	v_readlane_b32 s4, v234, 46
	s_lshl_b32 s4, s4, 7
	s_and_b32 s5, s50, 63
	s_add_i32 s4, s4, s5
	s_add_i32 s4, s4, 64
	s_lshl_b32 s4, s4, 6
	s_add_i32 s4, s4, 0x4000
	s_add_u32 s4, s92, s4
	s_addc_u32 s5, s93, 0
	v_mov_b32_e32 v0, 0
	s_waitcnt vmcnt(0) lgkmcnt(0)
	global_atomic_add v0, v210, s[4:5]
	s_waitcnt vmcnt(0)

; __device__ __forceinline__ int tid_opaque() { int t = threadIdx.x; asm volatile("" : "+v"(t)); return t; }
; __device__ __forceinline__ unsigned xb_ld(unsigned* p) { return __hip_atomic_load(p, __ATOMIC_RELAXED, __HIP_MEMORY_SCOPE_AGENT); }
; __device__ __forceinline__ unsigned xb_add(unsigned* p, unsigned v) { return __hip_atomic_fetch_add(p, v, __ATOMIC_RELAXED, __HIP_MEMORY_SCOPE_AGENT); }
; __device__ __forceinline__ void xcd_barrier(const XcdBarrier& b, unsigned epoch) {
;     asm volatile("s_waitcnt vmcnt(0)" ::: "memory");
;     __syncthreads();
;     if (tid_opaque() == 0) {
;         unsigned* bar = b.bar;
;         unsigned bx = b.x, bnloc = b.nloc, bnx = b.nx;
;         asm volatile("" : "+s"(bar), "+s"(bx), "+s"(bnloc), "+s"(bnx));
;         __builtin_amdgcn_s_waitcnt(0);
;         const unsigned old = xb_add(&bar[XB_XSUB(bx)], 1u);
;         const unsigned gen = epoch;
;         if (old + 1u == (gen + 1u) * bnloc) {
;             __builtin_amdgcn_fence(__ATOMIC_RELEASE, "agent");
;             asm volatile("s_waitcnt vmcnt(0)" ::: "memory");
;             const unsigned og = xb_add(&bar[XB_TOP], 1u);
;             const unsigned tg = epoch;
;             if (og + 1u == (tg + 1u) * bnx) xb_add(&bar[XB_TOPGEN], 1u);
;             else XB_SPIN(xb_ld(&bar[XB_TOPGEN]) == tg, bar);
;             __builtin_amdgcn_fence(__ATOMIC_ACQUIRE, "agent");
;             xb_add(&bar[XB_XGEN(bx)], 1u);
;         } else {
;             XB_SPIN(xb_ld(&bar[XB_XGEN(bx)]) == gen, bar);
;             __builtin_amdgcn_fence(__ATOMIC_ACQUIRE, "agent");
;         }
;     }
;     __syncthreads();
; }
.Lgbb_done:
	buffer_inv sc1
	s_branch .LBB0_512
	v_readlane_b32 s26, v234, 3
	s_mov_b64 s[2:3], s[92:93]
	v_readlane_b32 s6, v234, 2
	s_mov_b32 s4, s51
	s_lshl_b32 s24, s4, 6
	v_readlane_b32 s7, v234, 60
	s_add_i32 s72, s24, 0x500
	s_add_i32 s25, s7, 4
	s_lshl_b64 s[4:5], s[72:73], 2
	s_add_u32 s4, s2, s4
	s_addc_u32 s5, s3, s5
	v_mov_b64_e32 v[0:1], s[4:5]
	s_waitcnt vmcnt(0) expcnt(0) lgkmcnt(0)
	flat_atomic_add v0, v[0:1], v210 sc0
	s_add_i32 s27, s7, 5
	s_mul_i32 s6, s6, s27
	s_waitcnt vmcnt(0) lgkmcnt(0)
	v_add_u32_e32 v0, 1, v0
	v_cmp_ne_u32_e32 vcc, s6, v0
	s_and_saveexec_b64 s[4:5], vcc
	s_xor_b64 s[4:5], exec, s[4:5]
	s_cbranch_execz .LBB0_496
	s_add_i32 s72, s24, 0x900
	s_lshl_b64 s[6:7], s[72:73], 2
	s_add_u32 s8, s2, s6
	s_addc_u32 s9, s3, s7
	v_mov_b64_e32 v[0:1], s[8:9]
	flat_load_dword v0, v[0:1] sc1
	s_waitcnt vmcnt(0) lgkmcnt(0)
	v_cmp_eq_u32_e32 vcc, s25, v0
	s_and_saveexec_b64 s[6:7], vcc
	s_cbranch_execz .LBB0_495
	s_mov_b32 s28, 1
	s_mov_b64 s[10:11], 0
	s_branch .LBB0_487

; __device__ __forceinline__ int tid_opaque() { int t = threadIdx.x; asm volatile("" : "+v"(t)); return t; }
; __device__ __forceinline__ void phase_E(const Params& p, int l) {
;     const bf16_t* P1 = (const bf16_t*)(p.ws + WS_P1);
;     const float* PART = (const float*)(p.ws + WS_PART);
;     const float* xin = (l == 0) ? p.x : p.out;
;     const float* gpost = p.norm_post + l * 1024;
;     const int etid = tid_opaque(); const int lane = etid & 63, wv = etid >> 6;
;     const int nextra = (l == 0) ? NWT_IN : 0;
;     constexpr int RPW = 4;
;     constexpr int NIT = M_ / (8 * RPW);
;     for (int it = blockIdx.x; it < NIT + nextra; it += gridDim.x) {
;         if (it >= NIT) { convert_weights_tile(p, 1, it - NIT); continue; }
;         const int rowb = it * 8 * RPW + wv * RPW;
;         float ps[RPW]; uint2 ov[RPW][4]; float4 xv[RPW][4];
; #pragma unroll
;         for (int r = 0; r < RPW; ++r) {
;             const int row = rowb + r;
;             ps[r] = (lane < 16) ? PART[(long)row * 16 + lane] : 0.f;
; #pragma unroll
;             for (int i = 0; i < 4; ++i) {
;                 const int c = lane * 4 + 256 * i;
;                 ov[r][i] = ld_nt_u2(P1 + (long)row * P1W + 2560 + c);
;                 xv[r][i] = ld_nt_f4(xin + (long)row * 1024 + c);
;             }
;         }
.LBB0_512:
	s_or_b64 exec, exec, s[0:1]
	v_readlane_b32 s4, v234, 47
	v_readlane_b32 s5, v234, 48
	s_and_b64 s[0:1], s[4:5], exec
	s_movk_i32 s0, 0x3e0
	s_cselect_b32 s2, s0, 0x200
	s_mov_b64 s[0:1], s[4:5]
	v_mov_b32_e32 v0, v208
	s_cmp_ge_i32 s50, s2
	s_waitcnt lgkmcnt(0)
	s_barrier
	s_cbranch_scc1 .LBB0_542
	v_readlane_b32 s4, v234, 28
	s_and_b64 s[0:1], s[0:1], exec
	v_readlane_b32 s5, v234, 29
	s_mov_b64 s[0:1], s[4:5]
	v_readlane_b32 s3, v234, 46
	s_cselect_b32 s1, s1, s45
	s_cselect_b32 s0, s0, s44
	s_lshl_b32 s72, s3, 10
	s_lshl_b64 s[4:5], s[72:73], 2
	v_and_b32_e32 v2, 63, v0
	s_add_u32 s4, s42, s4
	s_addc_u32 s5, s43, s5
	v_lshlrev_b32_e32 v80, 2, v2
	v_lshlrev_b32_e32 v128, 4, v2
	v_ashrrev_i32_e32 v0, 4, v0
	v_lshl_add_u64 v[84:85], s[4:5], 0, v[128:129]
	v_or_b32_e32 v86, 0x100, v80
	v_readlane_b32 s4, v234, 26
	v_and_b32_e32 v3, -4, v0
	v_or_b32_e32 v88, 0x200, v80
	v_readlane_b32 s5, v234, 27
	v_lshlrev_b32_e32 v0, 2, v86
	v_mov_b32_e32 v1, v129
	v_or_b32_e32 v90, 0x300, v80
	v_lshl_add_u64 v[94:95], s[4:5], 0, v[0:1]
	v_lshlrev_b32_e32 v0, 2, v88
	v_readlane_b32 s6, v234, 30
	v_readlane_b32 s7, v234, 31
	v_mov_b32_e32 v81, v129
	v_lshl_add_u64 v[92:93], s[4:5], 0, v[128:129]
	v_lshl_add_u64 v[96:97], s[4:5], 0, v[0:1]
	v_lshlrev_b32_e32 v0, 2, v90
	v_lshl_add_u64 v[100:101], s[0:1], 0, v[128:129]
	v_lshlrev_b32_e32 v128, 3, v2
	s_and_b32 s98, s50, 7
	s_lshl_b32 s98, s98, 11
	s_lshr_b32 s99, s50, 3
	s_and_b32 s99, s99, 7
	s_lshl_b32 s99, s99, 8
	s_add_i32 s98, s98, s99
	s_lshr_b32 s99, s50, 6
	s_lshl_b32 s99, s99, 6
	s_add_i32 s0, s98, s99
	v_cmp_gt_u32_e64 s[6:7], 16, v2
	v_lshl_add_u64 v[82:83], s[96:97], 0, v[80:81]
	v_lshl_add_u64 v[98:99], s[4:5], 0, v[0:1]
	v_lshl_add_u64 v[102:103], s[74:75], 0, v[128:129]
	v_add_u32_e32 v104, s0, v3
	s_mov_b32 s3, s50
	v_readlane_b32 s8, v234, 32
	v_readlane_b32 s9, v234, 33
	v_readlane_b32 s10, v234, 34
	v_readlane_b32 s11, v234, 35
	s_branch .LBB0_517

; __device__ __forceinline__ void phase_E(const Params& p, int l) {
;     ...
;     for (int it = blockIdx.x; it < NIT + nextra; it += gridDim.x) {
;         if (it >= NIT) { convert_weights_tile(p, 1, it - NIT); continue; }
;         const int rowb = it * 8 * RPW + wv * RPW;
.LBB0_516:
	s_add_i32 s3, s3, s54
	s_movk_i32 s0, 32
	s_cmp_lt_i32 s3, s2
	s_nop 0
	v_add_u32_e32 v104, s0, v104
	s_cbranch_scc0 .LBB0_541

; __device__ __forceinline__ int tid_opaque() { int t = threadIdx.x; asm volatile("" : "+v"(t)); return t; }
; __device__ __forceinline__ unsigned xb_ld(unsigned* p) { return __hip_atomic_load(p, __ATOMIC_RELAXED, __HIP_MEMORY_SCOPE_AGENT); }
; __device__ __forceinline__ unsigned xb_add(unsigned* p, unsigned v) { return __hip_atomic_fetch_add(p, v, __ATOMIC_RELAXED, __HIP_MEMORY_SCOPE_AGENT); }
; __device__ __forceinline__ void xcd_barrier(const XcdBarrier& b, unsigned epoch) {
;     asm volatile("s_waitcnt vmcnt(0)" ::: "memory");
;     __syncthreads();
;     if (tid_opaque() == 0) {
;         unsigned* bar = b.bar;
;         unsigned bx = b.x, bnloc = b.nloc, bnx = b.nx;
;         asm volatile("" : "+s"(bar), "+s"(bx), "+s"(bnloc), "+s"(bnx));
;         __builtin_amdgcn_s_waitcnt(0);
;         const unsigned old = xb_add(&bar[XB_XSUB(bx)], 1u);
;         const unsigned gen = epoch;
;         if (old + 1u == (gen + 1u) * bnloc) {
;             __builtin_amdgcn_fence(__ATOMIC_RELEASE, "agent");
;             asm volatile("s_waitcnt vmcnt(0)" ::: "memory");
;             const unsigned og = xb_add(&bar[XB_TOP], 1u);
;             const unsigned tg = epoch;
;             if (og + 1u == (tg + 1u) * bnx) xb_add(&bar[XB_TOPGEN], 1u);
;             else XB_SPIN(xb_ld(&bar[XB_TOPGEN]) == tg, bar);
;             __builtin_amdgcn_fence(__ATOMIC_ACQUIRE, "agent");
;             xb_add(&bar[XB_XGEN(bx)], 1u);
;         } else {
;             XB_SPIN(xb_ld(&bar[XB_XGEN(bx)]) == gen, bar);
; __global__ void __launch_bounds__(512, 2) mega(Params p) {
;     ...
;         if (l == 0) xcd_barrier(xb, e0 + 4u);
.LBB0_542:
	s_andn2_b64 vcc, exec, s[0:1]
	s_mov_b64 s[0:1], -1
	s_cbranch_vccnz .LBB0_79
	s_waitcnt vmcnt(0)
	v_mov_b32_e32 v0, v208
	s_barrier
	s_nop 0
	v_cmp_eq_u32_e32 vcc, 0, v0
	s_and_saveexec_b64 s[0:1], vcc
	s_cbranch_execz .LBB0_78
	s_mov_b32 s4, s51
	v_readlane_b32 s25, v234, 3
	s_mov_b64 s[2:3], s[92:93]
	v_readlane_b32 s6, v234, 2
	s_lshl_b32 s24, s4, 6
	s_add_i32 s72, s24, 0x500
	s_lshl_b64 s[4:5], s[72:73], 2
	s_add_u32 s4, s2, s4
	s_addc_u32 s5, s3, s5
	v_mov_b64_e32 v[0:1], s[4:5]
	s_waitcnt vmcnt(0) expcnt(0) lgkmcnt(0)
	flat_atomic_add v0, v[0:1], v210 sc0
	s_mul_i32 s6, s6, 4
	s_waitcnt vmcnt(0) lgkmcnt(0)
	v_add_u32_e32 v0, 1, v0
	v_cmp_ne_u32_e32 vcc, s6, v0
	s_and_saveexec_b64 s[4:5], vcc
	s_xor_b64 s[4:5], exec, s[4:5]
	s_cbranch_execz .LBB0_557
	s_add_i32 s72, s24, 0x900
	s_lshl_b64 s[6:7], s[72:73], 2
	s_add_u32 s8, s2, s6
	s_addc_u32 s9, s3, s7
	v_mov_b64_e32 v[0:1], s[8:9]
	flat_load_dword v0, v[0:1] sc1
	s_waitcnt vmcnt(0) lgkmcnt(0)
	v_cmp_eq_u32_e32 vcc, 3, v0
	s_and_saveexec_b64 s[6:7], vcc
	s_cbranch_execz .LBB0_556
	s_mov_b32 s26, 1
	s_mov_b64 s[10:11], 0
	s_branch .LBB0_548

; __device__ __forceinline__ unsigned xb_ld(unsigned* p) { return __hip_atomic_load(p, __ATOMIC_RELAXED, __HIP_MEMORY_SCOPE_AGENT); }
; __device__ __forceinline__ void xcd_barrier(const XcdBarrier& b, unsigned epoch) {
;     ...
;             XB_SPIN(xb_ld(&bar[XB_XGEN(bx)]) == gen, bar);
.LBB0_552:
	s_andn2_b64 s[14:15], s[14:15], exec
	s_and_b64 s[20:21], s[20:21], exec
	s_or_b64 s[14:15], s[14:15], s[20:21]
	s_and_saveexec_b64 s[20:21], s[18:19]
	s_cbranch_execz .LBB0_547
	v_mov_b64_e32 v[0:1], s[8:9]
	flat_load_dword v0, v[0:1] sc1
	s_add_i32 s26, s26, 1
	s_or_b64 s[14:15], s[14:15], exec
	s_waitcnt vmcnt(0) lgkmcnt(0)
	v_cmp_ne_u32_e32 vcc, 3, v0
	s_orn2_b64 s[16:17], vcc, exec
	s_branch .LBB0_547

; __device__ __forceinline__ unsigned xb_ld(unsigned* p) { return __hip_atomic_load(p, __ATOMIC_RELAXED, __HIP_MEMORY_SCOPE_AGENT); }
; __device__ __forceinline__ unsigned xb_add(unsigned* p, unsigned v) { return __hip_atomic_fetch_add(p, v, __ATOMIC_RELAXED, __HIP_MEMORY_SCOPE_AGENT); }
; __device__ __forceinline__ void xcd_barrier(const XcdBarrier& b, unsigned epoch) {
;     ...
;         const unsigned old = xb_add(&bar[XB_XSUB(bx)], 1u);
;         const unsigned gen = epoch;
;         if (old + 1u == (gen + 1u) * bnloc) {
;             __builtin_amdgcn_fence(__ATOMIC_RELEASE, "agent");
;             asm volatile("s_waitcnt vmcnt(0)" ::: "memory");
;             const unsigned og = xb_add(&bar[XB_TOP], 1u);
;             const unsigned tg = epoch;
;             if (og + 1u == (tg + 1u) * bnx) xb_add(&bar[XB_TOPGEN], 1u);
;             else XB_SPIN(xb_ld(&bar[XB_TOPGEN]) == tg, bar);
;             __builtin_amdgcn_fence(__ATOMIC_ACQUIRE, "agent");
;             xb_add(&bar[XB_XGEN(bx)], 1u);
.LBB0_557:
	s_andn2_saveexec_b64 s[4:5], s[4:5]
	s_cbranch_execz .LBB0_78
	v_mov_b32_e32 v0, s2
	v_add_co_u32_e32 v0, vcc, 0x3000, v0
	v_mov_b32_e32 v1, s3
	buffer_wbl2 sc1
	s_waitcnt vmcnt(0)
	v_addc_co_u32_e32 v1, vcc, 0, v1, vcc
	flat_atomic_add v0, v[0:1], v210 offset:1024 sc0
	s_add_u32 s4, s2, 0x3500
	s_mul_i32 s25, s25, 4
	s_addc_u32 s5, s3, 0
	s_mov_b64 s[8:9], -1
	s_waitcnt vmcnt(0) lgkmcnt(0)
	v_add_u32_e32 v0, 1, v0
	v_cmp_ne_u32_e32 vcc, s25, v0
	v_mov_b64_e32 v[0:1], s[4:5]
	s_and_saveexec_b64 s[6:7], vcc
	s_cbranch_execz .LBB0_570
	v_mov_b64_e32 v[0:1], s[4:5]
	flat_load_dword v0, v[0:1] sc1
	s_mov_b64 s[12:13], 0
	s_waitcnt vmcnt(0) lgkmcnt(0)
	v_cmp_eq_u32_e32 vcc, 3, v0
	s_and_saveexec_b64 s[10:11], vcc
	s_cbranch_execz .LBB0_569
	s_add_u32 s8, s2, 0x200
	s_addc_u32 s9, s3, 0
	s_mov_b32 s25, 1
	s_branch .LBB0_562

; __device__ __forceinline__ unsigned xb_ld(unsigned* p) { return __hip_atomic_load(p, __ATOMIC_RELAXED, __HIP_MEMORY_SCOPE_AGENT); }
; __device__ __forceinline__ void xcd_barrier(const XcdBarrier& b, unsigned epoch) {
;     ...
;             else XB_SPIN(xb_ld(&bar[XB_TOPGEN]) == tg, bar);
.LBB0_567:
	v_mov_b64_e32 v[0:1], s[4:5]
	flat_load_dword v0, v[0:1] sc1
	s_add_i32 s25, s25, 1
	s_or_b64 s[18:19], s[18:19], exec
	s_waitcnt vmcnt(0) lgkmcnt(0)
	v_cmp_ne_u32_e32 vcc, 3, v0
	s_orn2_b64 s[16:17], vcc, exec
	s_branch .LBB0_561

; __global__ void __launch_bounds__(512, 2) mega(Params p) {
;     cg::grid_group grid = cg::this_grid();
;     ...
;     phase_prep(p);
;     if (p.never) grid.sync();
;     xcd_barrier(xb, 0u);
; #pragma unroll 1
;     for (int l = 0; l < 2; ++l) {
;         const unsigned e0 = 1u + 5u * (unsigned)l;
;         phase_A(p, l);
;         xcd_barrier(xb, e0);
;         phase_B(p, l);
;         xcd_barrier(xb, e0 + 1u);
;         phase_GC(p, l);
;         xcd_barrier(xb, e0 + 2u);
;         phase_D(p, l);
;         xcd_barrier(xb, e0 + 3u);
;         phase_E(p, l);
;         if (l == 0) xcd_barrier(xb, e0 + 4u);
;     }
; }
	.amdhsa_kernel _Z4mega6Params
		.amdhsa_group_segment_fixed_size 0
		.amdhsa_private_segment_fixed_size 0
		.amdhsa_kernarg_size 400
		.amdhsa_user_sgpr_count 2
		.amdhsa_user_sgpr_dispatch_ptr 0
		.amdhsa_user_sgpr_queue_ptr 0
		.amdhsa_user_sgpr_kernarg_segment_ptr 1
		.amdhsa_user_sgpr_dispatch_id 0
		.amdhsa_user_sgpr_kernarg_preload_length 0
		.amdhsa_user_sgpr_kernarg_preload_offset 0
		.amdhsa_user_sgpr_private_segment_size 0
		.amdhsa_uses_dynamic_stack 0
		.amdhsa_enable_private_segment 0
		.amdhsa_system_sgpr_workgroup_id_x 1
		.amdhsa_system_sgpr_workgroup_id_y 0
		.amdhsa_system_sgpr_workgroup_id_z 0
		.amdhsa_system_sgpr_workgroup_info 0
		.amdhsa_system_vgpr_workitem_id 2
		.amdhsa_next_free_vgpr 235
		.amdhsa_next_free_sgpr 102
		.amdhsa_accum_offset 236
		.amdhsa_reserve_vcc 1
		.amdhsa_float_round_mode_32 0
		.amdhsa_float_round_mode_16_64 0
		.amdhsa_float_denorm_mode_32 3
		.amdhsa_float_denorm_mode_16_64 3
		.amdhsa_dx10_clamp 1
		.amdhsa_ieee_mode 1
		.amdhsa_fp16_overflow 0
		.amdhsa_tg_split 0
		.amdhsa_exception_fp_ieee_invalid_op 0
		.amdhsa_exception_fp_denorm_src 0
		.amdhsa_exception_fp_ieee_div_zero 0
		.amdhsa_exception_fp_ieee_overflow 0
		.amdhsa_exception_fp_ieee_underflow 0
		.amdhsa_exception_fp_ieee_inexact 0
		.amdhsa_exception_int_div_zero 0
	.end_amdhsa_kernel

; __global__ void __launch_bounds__(512, 2) mega(Params p) {
amdhsa.kernels:
  - .agpr_count:     0
    .args:
      - .offset:         0
        .size:           144
        .value_kind:     by_value
      - .offset:         144
        .size:           4
        .value_kind:     hidden_block_count_x
      - .offset:         148
        .size:           4
        .value_kind:     hidden_block_count_y
      - .offset:         152
        .size:           4
        .value_kind:     hidden_block_count_z
      - .offset:         156
        .size:           2
        .value_kind:     hidden_group_size_x
      - .offset:         158
        .size:           2
        .value_kind:     hidden_group_size_y
      - .offset:         160
        .size:           2
        .value_kind:     hidden_group_size_z
      - .offset:         162
        .size:           2
        .value_kind:     hidden_remainder_x
      - .offset:         164
        .size:           2
        .value_kind:     hidden_remainder_y
      - .offset:         166
        .size:           2
        .value_kind:     hidden_remainder_z
      - .offset:         184
        .size:           8
        .value_kind:     hidden_global_offset_x
      - .offset:         192
        .size:           8
        .value_kind:     hidden_global_offset_y
      - .offset:         200
        .size:           8
        .value_kind:     hidden_global_offset_z
      - .offset:         208
        .size:           2
        .value_kind:     hidden_grid_dims
      - .offset:         232
        .size:           8
        .value_kind:     hidden_multigrid_sync_arg
      - .offset:         264
        .size:           4
        .value_kind:     hidden_dynamic_lds_size
    .group_segment_fixed_size: 0
    .kernarg_segment_align: 8
    .kernarg_segment_size: 400
    .language:       OpenCL C
    .language_version:
      - 2
      - 0
    .max_flat_workgroup_size: 512
    .name:           _Z4mega6Params
    .private_segment_fixed_size: 0
    .sgpr_count:     108
    .sgpr_spill_count: 64
    .symbol:         _Z4mega6Params.kd
    .uniform_work_group_size: 1
    .uses_dynamic_stack: false
    .vgpr_count:     235
    .vgpr_spill_count: 0
    .wavefront_size: 64
